# opt19: row-wise norm phases: 64-lane sums by DPP row ops + readlane instead of six ds_bpermute round trips
# speedup vs baseline: 1.0055x; 1.0055x over previous
; template <bool HAS_H, bool HAS_XN, int XL, int XS>
; __device__ __forceinline__ void rowwise_phase(const float* xf, half_t* x16, float* xo, const half_t* hs, const float* nwA, const float* gvec, const float* nwB, const float* scv, const float* shv, half_t* xn, int gw, int NW, int lane) {
;     ...
;             const int mn = (m + NW < mend) ? m + NW : m;
;             {
;                 if (XL == 0) { const f32x4* xr = (const f32x4*)(xf + (size_t)mn * D) + lane;
; #pragma unroll
;                     for (int j = 0; j < 4; ++j) xq[j] = xr[64 * j]; }
;                 else { const half4* xr = (const half4*)(x16 + (size_t)mn * D) + lane;
; #pragma unroll
;                     for (int j = 0; j < 4; ++j) xh[j] = xr[64 * j]; }
;                 if (HAS_H) { const half4* hr = (const half4*)(hs + (size_t)mn * D) + lane;
; #pragma unroll
;                     for (int j = 0; j < 4; ++j) hq[j] = hr[64 * j]; }
;             }
;             if (HAS_H) {
;                 f32x4 hv[4]; float ss = 0.f;
; #pragma unroll
;                 for (int j = 0; j < 4; ++j) { const half4 h4 = hcur[j]; hv[j] = (f32x4){(float)h4[0], (float)h4[1], (float)h4[2], (float)h4[3]}; ss += (hv[j][0] * hv[j][0] + hv[j][1] * hv[j][1]) + (hv[j][2] * hv[j][2] + hv[j][3] * hv[j][3]); }
;                 const float r = 1.0f / sqrtf(wave_sum(ss) * (1.f / D) + RMS_EPS);
.LBB0_1234:
	v_cvt_f32_f16_sdwa v147, v114 dst_sel:DWORD dst_unused:UNUSED_PAD src0_sel:WORD_1
	v_cvt_f32_f16_sdwa v149, v115 dst_sel:DWORD dst_unused:UNUSED_PAD src0_sel:WORD_1
	v_cvt_f32_f16_e32 v146, v114
	v_cvt_f32_f16_e32 v148, v115
	v_mov_b32_e32 v150, v147
	v_mov_b32_e32 v151, v149
	v_mov_b32_e32 v114, v146
	v_mov_b32_e32 v115, v148
	v_pk_mul_f32 v[150:151], v[150:151], v[150:151]
	v_cvt_f32_f16_sdwa v153, v113 dst_sel:DWORD dst_unused:UNUSED_PAD src0_sel:WORD_1
	v_pk_fma_f32 v[114:115], v[114:115], v[114:115], v[150:151]
	v_cvt_f32_f16_sdwa v151, v112 dst_sel:DWORD dst_unused:UNUSED_PAD src0_sel:WORD_1
	v_cvt_f32_f16_e32 v150, v112
	v_cvt_f32_f16_e32 v152, v113
	v_mov_b32_e32 v155, v153
	v_mov_b32_e32 v154, v151
	v_mov_b32_e32 v112, v150
	v_mov_b32_e32 v113, v152
	v_pk_mul_f32 v[154:155], v[154:155], v[154:155]
	v_cvt_f32_f16_e32 v156, v111
	v_pk_fma_f32 v[112:113], v[112:113], v[112:113], v[154:155]
	v_cvt_f32_f16_e32 v154, v110
	v_cvt_f32_f16_sdwa v155, v110 dst_sel:DWORD dst_unused:UNUSED_PAD src0_sel:WORD_1
	v_cvt_f32_f16_sdwa v157, v111 dst_sel:DWORD dst_unused:UNUSED_PAD src0_sel:WORD_1
	v_cvt_f32_f16_sdwa v161, v108 dst_sel:DWORD dst_unused:UNUSED_PAD src0_sel:WORD_1
	v_cvt_f32_f16_e32 v160, v108
	v_cvt_f32_f16_sdwa v163, v109 dst_sel:DWORD dst_unused:UNUSED_PAD src0_sel:WORD_1
	v_cvt_f32_f16_e32 v162, v109
	v_mul_f32_e32 v110, v154, v154
	v_pk_fma_f32 v[110:111], v[154:155], v[154:155], v[110:111] op_sel_hi:[1,1,0]
	v_pk_add_f32 v[114:115], v[114:115], v[114:115] op_sel_hi:[0,1]
	v_mul_f32_e32 v110, v156, v156
	v_pk_add_f32 v[112:113], v[112:113], v[112:113] op_sel_hi:[0,1]
	v_pk_fma_f32 v[158:159], v[156:157], v[156:157], v[110:111] op_sel_hi:[1,1,0]
	v_pk_mul_f32 v[108:109], v[160:161], v[160:161]
	v_pk_mul_f32 v[164:165], v[162:163], v[162:163]
	v_mov_b32_e32 v110, v108
	v_mov_b32_e32 v158, v109
	v_mov_b32_e32 v114, v164
	v_mov_b32_e32 v112, v165
	v_pk_add_f32 v[108:109], v[110:111], v[158:159]
	v_pk_add_f32 v[110:111], v[114:115], v[112:113]
	s_add_i32 s3, s20, s80
	v_pk_add_f32 v[108:109], v[108:109], v[110:111]
	s_cmp_lt_i32 s3, s2
	v_add_f32_e32 v108, v108, v109
	s_cselect_b32 s4, s3, s20
	s_ashr_i32 s5, s4, 31
	s_lshl_b64 s[4:5], s[4:5], 11
	v_cvt_f32_f16_sdwa v133, v100 dst_sel:DWORD dst_unused:UNUSED_PAD src0_sel:WORD_1
	s_nop 1
	v_add_f32_dpp v108, v108, v108 quad_perm:[1,0,3,2] row_mask:0xf bank_mask:0xf
	v_cvt_f32_f16_e32 v132, v100
	v_lshl_add_u64 v[100:101], v[94:95], 0, s[4:5]
	v_lshl_add_u64 v[116:117], v[96:97], 0, s[4:5]
	v_cvt_f32_f16_sdwa v127, v103 dst_sel:DWORD dst_unused:UNUSED_PAD src0_sel:WORD_1
	s_nop 1
	v_add_f32_dpp v108, v108, v108 quad_perm:[2,3,0,1] row_mask:0xf bank_mask:0xf
	v_cvt_f32_f16_e32 v126, v103
	v_cvt_f32_f16_sdwa v125, v102 dst_sel:DWORD dst_unused:UNUSED_PAD src0_sel:WORD_1
	v_cvt_f32_f16_e32 v124, v102
	v_cvt_f32_f16_sdwa v135, v105 dst_sel:DWORD dst_unused:UNUSED_PAD src0_sel:WORD_1
	s_nop 1
	v_add_f32_dpp v108, v108, v108 row_half_mirror row_mask:0xf bank_mask:0xf
	v_cvt_f32_f16_e32 v134, v105
	v_cvt_f32_f16_sdwa v129, v104 dst_sel:DWORD dst_unused:UNUSED_PAD src0_sel:WORD_1
	v_cvt_f32_f16_e32 v128, v104
	v_cvt_f32_f16_sdwa v137, v99 dst_sel:DWORD dst_unused:UNUSED_PAD src0_sel:WORD_1
	s_nop 1
	v_add_f32_dpp v108, v108, v108 row_mirror row_mask:0xf bank_mask:0xf
	v_cvt_f32_f16_e32 v136, v99
	v_cvt_f32_f16_sdwa v131, v98 dst_sel:DWORD dst_unused:UNUSED_PAD src0_sel:WORD_1
	v_cvt_f32_f16_e32 v130, v98
	v_cvt_f32_f16_sdwa v145, v143 dst_sel:DWORD dst_unused:UNUSED_PAD src0_sel:WORD_1
	s_nop 1
	v_add_f32_dpp v108, v108, v108 row_bcast:15 row_mask:0xa bank_mask:0xf
	v_cvt_f32_f16_e32 v144, v143
	global_load_dwordx2 v[102:103], v[100:101], off
	global_load_dwordx2 v[104:105], v[100:101], off offset:512
	global_load_dwordx2 v[98:99], v[100:101], off offset:1024
	s_nop 0
	global_load_dwordx2 v[100:101], v[100:101], off offset:1536
	s_nop 0
	global_load_dwordx2 v[122:123], v[116:117], off
	global_load_dwordx2 v[120:121], v[116:117], off offset:512
	global_load_dwordx2 v[118:119], v[116:117], off offset:1024
	s_nop 0
	global_load_dwordx2 v[116:117], v[116:117], off offset:1536
	s_cmp_ge_i32 s3, s2
	s_nop 1
	v_add_f32_dpp v108, v108, v108 row_bcast:31 row_mask:0xc bank_mask:0xf
	s_nop 0
	v_readlane_b32 s100, v108, 63
	s_nop 1
	v_mov_b32_e32 v108, s100
	v_fmamk_f32 v108, v108, 0x3a800000, v201
	v_cmp_gt_f32_e32 vcc, s81, v108
	v_mul_f32_e32 v109, 0x4f800000, v108
	s_mov_b32 s20, s3
	v_cndmask_b32_e32 v108, v108, v109, vcc
	v_sqrt_f32_e32 v109, v108
	s_nop 0
	v_add_u32_e32 v110, -1, v109
	v_fma_f32 v111, -v110, v109, v108
	v_cmp_ge_f32_e64 s[4:5], 0, v111
	v_add_u32_e32 v111, 1, v109
	s_nop 0
	v_cndmask_b32_e64 v110, v109, v110, s[4:5]
	v_fma_f32 v109, -v111, v109, v108
	v_cmp_lt_f32_e64 s[4:5], 0, v109
	s_nop 1
	v_cndmask_b32_e64 v109, v110, v111, s[4:5]
	v_mul_f32_e32 v110, 0x37800000, v109
	v_cndmask_b32_e32 v109, v109, v110, vcc
	v_cmp_class_f32_e32 vcc, v108, v202
	s_nop 1
	v_cndmask_b32_e32 v108, v109, v108, vcc
	v_div_scale_f32 v109, s[4:5], v108, v108, 1.0
	v_rcp_f32_e32 v110, v109
	s_nop 0
	v_fma_f32 v111, -v109, v110, 1.0
	v_fmac_f32_e32 v110, v111, v110
	v_div_scale_f32 v111, vcc, 1.0, v108, 1.0
	v_mul_f32_e32 v112, v111, v110
	v_fma_f32 v113, -v109, v112, v111
	v_fmac_f32_e32 v112, v113, v110
	v_fma_f32 v109, -v109, v112, v111
	v_div_fmas_f32 v109, v109, v110, v112
	v_div_fixup_f32 v108, v109, v108, 1.0
	v_pk_mul_f32 v[110:111], v[148:149], v[108:109] op_sel_hi:[1,0]
	v_pk_mul_f32 v[112:113], v[146:147], v[108:109] op_sel_hi:[1,0]
	v_pk_mul_f32 v[110:111], v[4:5], v[110:111]
	v_pk_mul_f32 v[112:113], v[2:3], v[112:113]
	v_pk_fma_f32 v[146:147], v[12:13], v[110:111], v[126:127]
; template <bool HAS_H, bool HAS_XN, int XL, int XS>
; __device__ __forceinline__ void rowwise_phase(const float* xf, half_t* x16, float* xo, const half_t* hs, const float* nwA, const float* gvec, const float* nwB, const float* scv, const float* shv, half_t* xn, int gw, int NW, int lane) {
;     ...
;                 for (int j = 0; j < 4; ++j) xv[j] = xv[j] + gg[j] * (hv[j] * r * wA[j]);
;             }
;             if (XS == 1) {
;                 u32x2* xs = (u32x2*)(x16 + (size_t)m * D) + lane;
; #pragma unroll
;                 for (int j = 0; j < 4; ++j) { u32x2 pk; pk.x = pg8::pkh(xv[j][0], xv[j][1]); pk.y = pg8::pkh(xv[j][2], xv[j][3]); xs[64 * j] = pk; }
;             } else if (XS == 2) {
;                 f32x4* xs = (f32x4*)(xo + (size_t)m * D) + lane;
; #pragma unroll
;                 for (int j = 0; j < 4; ++j) xs[64 * j] = xv[j];
;             }
;             if (HAS_XN) {
;                 float ss = 0.f;
; #pragma unroll
;                 for (int j = 0; j < 4; ++j) ss += (xv[j][0] * xv[j][0] + xv[j][1] * xv[j][1]) + (xv[j][2] * xv[j][2] + xv[j][3] * xv[j][3]);
;                 const float r = 1.0f / sqrtf(wave_sum(ss) * (1.f / D) + RMS_EPS);
;                 u32x2* xo2 = (u32x2*)(xn + (size_t)m * D) + lane;
; #pragma unroll
;                 for (int j = 0; j < 4; ++j) { const f32x4 o = (xv[j] * r * wB[j]) * sc1[j] + sh[j]; u32x2 pk; pk.x = pg8::pkh(o[0], o[1]); pk.y = pg8::pkh(o[2], o[3]); xo2[64 * j] = pk; }
	v_pk_mul_f32 v[110:111], v[152:153], v[108:109] op_sel_hi:[1,0]
	v_pk_fma_f32 v[148:149], v[10:11], v[112:113], v[124:125]
	v_pk_mul_f32 v[112:113], v[150:151], v[108:109] op_sel_hi:[1,0]
	v_pk_mul_f32 v[110:111], v[8:9], v[110:111]
	v_pk_mul_f32 v[112:113], v[6:7], v[112:113]
	v_pk_fma_f32 v[126:127], v[16:17], v[110:111], v[134:135]
	v_pk_mul_f32 v[110:111], v[156:157], v[108:109] op_sel_hi:[1,0]
	v_pk_fma_f32 v[128:129], v[14:15], v[112:113], v[128:129]
	v_pk_mul_f32 v[112:113], v[154:155], v[108:109] op_sel_hi:[1,0]
	v_pk_mul_f32 v[110:111], v[36:37], v[110:111]
	v_pk_mul_f32 v[114:115], v[34:35], v[112:113]
	v_pk_fma_f32 v[112:113], v[44:45], v[110:111], v[136:137]
	v_pk_mul_f32 v[110:111], v[162:163], v[108:109] op_sel_hi:[1,0]
	v_pk_mul_f32 v[108:109], v[160:161], v[108:109] op_sel_hi:[1,0]
	v_pk_fma_f32 v[114:115], v[42:43], v[114:115], v[130:131]
	v_pk_mul_f32 v[124:125], v[38:39], v[108:109]
	v_pk_mul_f32 v[108:109], v[40:41], v[110:111]
	v_pk_fma_f32 v[110:111], v[46:47], v[124:125], v[132:133]
	v_cvt_pk_f16_f32 v210, v148, v149
	v_cvt_pk_f16_f32 v211, v146, v147
	v_cvt_pk_f16_f32 v212, v128, v129
	v_cvt_pk_f16_f32 v213, v126, v127
	v_pk_fma_f32 v[108:109], v[48:49], v[108:109], v[144:145]
	v_cvt_pk_f16_f32 v214, v114, v115
	v_cvt_pk_f16_f32 v215, v112, v113
	v_cvt_pk_f16_f32 v216, v110, v111
	v_cvt_pk_f16_f32 v217, v108, v109
	v_pk_mul_f32 v[124:125], v[146:147], v[146:147]
	v_pk_mul_f32 v[130:131], v[148:149], v[148:149]
	s_nop 0
	v_pk_mov_b32 v[132:133], v[130:131], v[124:125] op_sel:[1,0]
	v_mov_b32_e32 v131, v125
	v_pk_add_f32 v[124:125], v[132:133], v[130:131]
	v_pk_mul_f32 v[130:131], v[126:127], v[126:127]
	v_pk_add_f32 v[124:125], v[124:125], v[124:125] op_sel_hi:[0,1]
	v_pk_mul_f32 v[132:133], v[128:129], v[128:129]
	v_mul_f32_e32 v124, v114, v114
	v_pk_mov_b32 v[134:135], v[132:133], v[130:131] op_sel:[1,0]
	v_mov_b32_e32 v133, v131
	v_pk_add_f32 v[130:131], v[134:135], v[132:133]
	v_pk_fma_f32 v[132:133], v[114:115], v[114:115], v[124:125] op_sel_hi:[1,1,0]
	v_mul_f32_e32 v124, v112, v112
	v_pk_add_f32 v[130:131], v[130:131], v[130:131] op_sel_hi:[0,1]
	v_pk_fma_f32 v[134:135], v[112:113], v[112:113], v[124:125] op_sel_hi:[1,1,0]
	v_mul_f32_e32 v132, v110, v110
	v_mul_f32_e32 v134, v111, v111
	v_mul_f32_e32 v124, v108, v108
	v_mul_f32_e32 v130, v109, v109
	v_pk_add_f32 v[132:133], v[132:133], v[134:135]
	v_pk_add_f32 v[124:125], v[124:125], v[130:131]
	s_nop 0
	v_pk_add_f32 v[124:125], v[132:133], v[124:125]
	s_nop 0
	v_add_f32_e32 v124, v124, v125
	s_nop 1
	v_add_f32_dpp v124, v124, v124 quad_perm:[1,0,3,2] row_mask:0xf bank_mask:0xf
	s_nop 1
	v_add_f32_dpp v124, v124, v124 quad_perm:[2,3,0,1] row_mask:0xf bank_mask:0xf
	s_nop 1
	v_add_f32_dpp v124, v124, v124 row_half_mirror row_mask:0xf bank_mask:0xf
	s_nop 1
	v_add_f32_dpp v124, v124, v124 row_mirror row_mask:0xf bank_mask:0xf
	s_nop 1
	v_add_f32_dpp v124, v124, v124 row_bcast:15 row_mask:0xa bank_mask:0xf
	s_nop 1
	v_add_f32_dpp v124, v124, v124 row_bcast:31 row_mask:0xc bank_mask:0xf
	s_nop 0
	v_readlane_b32 s100, v124, 63
	s_nop 1
	v_mov_b32_e32 v124, s100
	v_fmamk_f32 v124, v124, 0x3a800000, v201
	v_cmp_gt_f32_e32 vcc, s81, v124
	v_mul_f32_e32 v125, 0x4f800000, v124
	s_nop 0
	v_cndmask_b32_e32 v124, v124, v125, vcc
	v_sqrt_f32_e32 v125, v124
	s_nop 0
	v_add_u32_e32 v130, -1, v125
	v_fma_f32 v131, -v130, v125, v124
	v_cmp_ge_f32_e64 s[4:5], 0, v131
	v_add_u32_e32 v131, 1, v125
	s_nop 0
	v_cndmask_b32_e64 v130, v125, v130, s[4:5]
	v_fma_f32 v125, -v131, v125, v124
	v_cmp_lt_f32_e64 s[4:5], 0, v125
	s_nop 1
	v_cndmask_b32_e64 v125, v130, v131, s[4:5]
	v_mul_f32_e32 v130, 0x37800000, v125
	v_cndmask_b32_e32 v125, v125, v130, vcc
	v_cmp_class_f32_e32 vcc, v124, v202
	s_nop 1
	v_cndmask_b32_e32 v124, v125, v124, vcc
	v_div_scale_f32 v125, s[4:5], v124, v124, 1.0
	v_rcp_f32_e32 v130, v125
	s_nop 0
	v_fma_f32 v131, -v125, v130, 1.0
	v_fmac_f32_e32 v130, v131, v130
	v_div_scale_f32 v131, vcc, 1.0, v124, 1.0
	v_mul_f32_e32 v132, v131, v130
	v_fma_f32 v133, -v125, v132, v131
	v_fmac_f32_e32 v132, v133, v130
	v_fma_f32 v125, -v125, v132, v131
	v_div_fmas_f32 v125, v125, v130, v132
	v_div_fixup_f32 v124, v125, v124, 1.0
	v_pk_mul_f32 v[130:131], v[146:147], v[124:125] op_sel_hi:[1,0]
	v_pk_mul_f32 v[132:133], v[148:149], v[124:125] op_sel_hi:[1,0]
	v_pk_mul_f32 v[130:131], v[20:21], v[130:131]
	v_pk_mul_f32 v[132:133], v[18:19], v[132:133]
	v_pk_mul_f32 v[126:127], v[126:127], v[124:125] op_sel_hi:[1,0]
	v_pk_mul_f32 v[128:129], v[128:129], v[124:125] op_sel_hi:[1,0]
	v_pk_fma_f32 v[134:135], v[80:81], v[130:131], v[28:29]
	v_pk_fma_f32 v[130:131], v[78:79], v[132:133], v[26:27]
	v_add_co_u32_e32 v132, vcc, s57, v106
	v_pk_mul_f32 v[128:129], v[22:23], v[128:129]
	v_pk_mul_f32 v[126:127], v[24:25], v[126:127]
	v_addc_co_u32_e32 v133, vcc, -1, v107, vcc
	v_pk_fma_f32 v[126:127], v[72:73], v[126:127], v[32:33]
	v_pk_fma_f32 v[128:129], v[70:71], v[128:129], v[30:31]
	v_pk_mul_f32 v[112:113], v[112:113], v[124:125] op_sel_hi:[1,0]
	v_pk_mul_f32 v[114:115], v[114:115], v[124:125] op_sel_hi:[1,0]
	v_cvt_pk_f16_f32 v128, v128, v129
	v_cvt_pk_f16_f32 v129, v126, v127
	v_add_co_u32_e32 v126, vcc, s67, v106
	v_pk_mul_f32 v[114:115], v[50:51], v[114:115]
	v_pk_mul_f32 v[112:113], v[52:53], v[112:113]
	v_addc_co_u32_e32 v127, vcc, -1, v107, vcc
	v_pk_fma_f32 v[112:113], v[76:77], v[112:113], v[60:61]
	v_pk_fma_f32 v[114:115], v[74:75], v[114:115], v[58:59]
	v_pk_mul_f32 v[108:109], v[108:109], v[124:125] op_sel_hi:[1,0]
	v_pk_mul_f32 v[110:111], v[110:111], v[124:125] op_sel_hi:[1,0]
	v_cvt_pk_f16_f32 v114, v114, v115
	v_cvt_pk_f16_f32 v115, v112, v113
	v_add_co_u32_e32 v112, vcc, s95, v106
	v_pk_mul_f32 v[110:111], v[54:55], v[110:111]
	v_pk_mul_f32 v[108:109], v[56:57], v[108:109]
	v_addc_co_u32_e32 v113, vcc, -1, v107, vcc
	v_pk_fma_f32 v[108:109], v[68:69], v[108:109], v[64:65]
	v_pk_fma_f32 v[110:111], v[66:67], v[110:111], v[62:63]
	v_cvt_pk_f16_f32 v130, v130, v131
	v_cvt_pk_f16_f32 v110, v110, v111
	v_cvt_pk_f16_f32 v111, v108, v109
	v_add_co_u32_e32 v108, vcc, s76, v106
	v_cvt_pk_f16_f32 v131, v134, v135
	s_nop 0
	v_addc_co_u32_e32 v109, vcc, -1, v107, vcc
	s_waitcnt vmcnt(0)
	v_mov_b32_e32 v143, v101
	global_store_dwordx2 v[106:107], v[210:211], off
	global_store_dwordx2 v[106:107], v[212:213], off offset:512
	global_store_dwordx2 v[106:107], v[214:215], off offset:1024
	global_store_dwordx2 v[106:107], v[216:217], off offset:1536
	global_store_dwordx2 v[112:113], v[114:115], off
	global_store_dwordx2 v[108:109], v[110:111], off
	v_mov_b32_e32 v114, v122
	v_mov_b32_e32 v115, v123
	v_mov_b32_e32 v112, v120
	v_mov_b32_e32 v113, v121
	v_mov_b32_e32 v110, v118
	v_mov_b32_e32 v111, v119
	v_mov_b32_e32 v108, v116
	v_mov_b32_e32 v109, v117
	v_lshl_add_u64 v[106:107], v[106:107], 0, s[90:91]
	global_store_dwordx2 v[132:133], v[130:131], off
	global_store_dwordx2 v[126:127], v[128:129], off
	s_cbranch_scc0 .LBB0_1234
	s_branch .LBB0_1229

; template <bool HAS_H, bool HAS_XN, int XL, int XS>
; __device__ __forceinline__ void rowwise_phase(const float* xf, half_t* x16, float* xo, const half_t* hs, const float* nwA, const float* gvec, const float* nwB, const float* scv, const float* shv, half_t* xn, int gw, int NW, int lane) {
;     ...
;                 if (XL == 0) { const f32x4* xr = (const f32x4*)(xf + (size_t)mn * D) + lane;
; #pragma unroll
;                     for (int j = 0; j < 4; ++j) xq[j] = xr[64 * j]; }
;                 else { const half4* xr = (const half4*)(x16 + (size_t)mn * D) + lane;
; #pragma unroll
;                     for (int j = 0; j < 4; ++j) xh[j] = xr[64 * j]; }
;                 if (HAS_H) { const half4* hr = (const half4*)(hs + (size_t)mn * D) + lane;
; #pragma unroll
;                     for (int j = 0; j < 4; ++j) hq[j] = hr[64 * j]; }
;             }
;             if (HAS_H) {
;                 f32x4 hv[4]; float ss = 0.f;
; #pragma unroll
;                 for (int j = 0; j < 4; ++j) { const half4 h4 = hcur[j]; hv[j] = (f32x4){(float)h4[0], (float)h4[1], (float)h4[2], (float)h4[3]}; ss += (hv[j][0] * hv[j][0] + hv[j][1] * hv[j][1]) + (hv[j][2] * hv[j][2] + hv[j][3] * hv[j][3]); }
;                 const float r = 1.0f / sqrtf(wave_sum(ss) * (1.f / D) + RMS_EPS);
.LBB0_1243:
	v_mov_b64_e32 v[152:153], v[114:115]
	v_cvt_f32_f16_sdwa v155, v152 dst_sel:DWORD dst_unused:UNUSED_PAD src0_sel:WORD_1
	v_cvt_f32_f16_sdwa v157, v153 dst_sel:DWORD dst_unused:UNUSED_PAD src0_sel:WORD_1
	v_cvt_f32_f16_e32 v154, v152
	v_cvt_f32_f16_e32 v156, v153
	v_mov_b32_e32 v158, v155
	v_mov_b32_e32 v159, v157
	v_mov_b64_e32 v[150:151], v[116:117]
	v_mov_b32_e32 v152, v154
	v_mov_b32_e32 v153, v156
	v_pk_mul_f32 v[158:159], v[158:159], v[158:159]
	v_cvt_f32_f16_sdwa v161, v151 dst_sel:DWORD dst_unused:UNUSED_PAD src0_sel:WORD_1
	v_pk_fma_f32 v[152:153], v[152:153], v[152:153], v[158:159]
	v_cvt_f32_f16_sdwa v159, v150 dst_sel:DWORD dst_unused:UNUSED_PAD src0_sel:WORD_1
	v_cvt_f32_f16_e32 v158, v150
	v_cvt_f32_f16_e32 v160, v151
	v_mov_b32_e32 v163, v161
	v_mov_b32_e32 v162, v159
	v_mov_b64_e32 v[142:143], v[118:119]
	v_mov_b32_e32 v150, v158
	v_mov_b32_e32 v151, v160
	v_pk_mul_f32 v[162:163], v[162:163], v[162:163]
	v_mov_b64_e32 v[140:141], v[120:121]
	v_pk_fma_f32 v[150:151], v[150:151], v[150:151], v[162:163]
	v_cvt_f32_f16_sdwa v163, v142 dst_sel:DWORD dst_unused:UNUSED_PAD src0_sel:WORD_1
	v_cvt_f32_f16_e32 v162, v142
	v_cvt_f32_f16_sdwa v165, v143 dst_sel:DWORD dst_unused:UNUSED_PAD src0_sel:WORD_1
	v_cvt_f32_f16_e32 v164, v143
	v_cvt_f32_f16_sdwa v169, v140 dst_sel:DWORD dst_unused:UNUSED_PAD src0_sel:WORD_1
	v_cvt_f32_f16_e32 v168, v140
	v_cvt_f32_f16_sdwa v181, v141 dst_sel:DWORD dst_unused:UNUSED_PAD src0_sel:WORD_1
	v_cvt_f32_f16_e32 v180, v141
	v_mul_f32_e32 v0, v163, v163
	v_pk_fma_f32 v[142:143], v[162:163], v[162:163], v[0:1] op_sel_hi:[1,1,0]
	v_mul_f32_e32 v0, v165, v165
	v_pk_add_f32 v[152:153], v[152:153], v[152:153] op_sel:[0,1] op_sel_hi:[1,0]
	v_pk_add_f32 v[150:151], v[150:151], v[150:151] op_sel:[0,1] op_sel_hi:[1,0]
	v_pk_fma_f32 v[166:167], v[164:165], v[164:165], v[0:1] op_sel_hi:[1,1,0]
	v_pk_mul_f32 v[140:141], v[168:169], v[168:169]
	v_pk_mul_f32 v[182:183], v[180:181], v[180:181]
	v_mov_b32_e32 v153, v140
	v_mov_b32_e32 v151, v141
	v_mov_b32_e32 v143, v182
	v_mov_b32_e32 v167, v183
	v_pk_add_f32 v[140:141], v[152:153], v[150:151]
	v_pk_add_f32 v[142:143], v[142:143], v[166:167]
	s_add_i32 s3, s10, s80
	v_pk_add_f32 v[140:141], v[140:141], v[142:143]
	s_cmp_lt_i32 s3, s2
	v_add_f32_e32 v0, v140, v141
	s_cselect_b32 s4, s3, s10
	s_ashr_i32 s5, s4, 31
	s_lshl_b64 s[10:11], s[4:5], 12
	s_lshl_b64 s[4:5], s[4:5], 11
	s_nop 1
	v_add_f32_dpp v0, v0, v0 quad_perm:[1,0,3,2] row_mask:0xf bank_mask:0xf
	v_lshl_add_u64 v[120:121], v[110:111], 0, s[4:5]
	v_lshl_add_u64 v[82:83], v[108:109], 0, s[10:11]
	global_load_dwordx4 v[94:97], v[82:83], off
	global_load_dwordx4 v[90:93], v[82:83], off offset:1024
	global_load_dwordx4 v[86:89], v[82:83], off offset:2048
	s_nop 0
	global_load_dwordx4 v[82:85], v[82:83], off offset:3072
	s_nop 0
	global_load_dwordx2 v[114:115], v[120:121], off
	global_load_dwordx2 v[116:117], v[120:121], off offset:512
	global_load_dwordx2 v[118:119], v[120:121], off offset:1024
	s_nop 0
	global_load_dwordx2 v[120:121], v[120:121], off offset:1536
	s_nop 1
	v_add_f32_dpp v0, v0, v0 quad_perm:[2,3,0,1] row_mask:0xf bank_mask:0xf
	s_cmp_ge_i32 s3, s2
	s_mov_b32 s10, s3
	s_nop 1
	v_add_f32_dpp v0, v0, v0 row_half_mirror row_mask:0xf bank_mask:0xf
	s_nop 1
	v_add_f32_dpp v0, v0, v0 row_mirror row_mask:0xf bank_mask:0xf
	s_nop 1
	v_add_f32_dpp v0, v0, v0 row_bcast:15 row_mask:0xa bank_mask:0xf
	s_nop 1
	v_add_f32_dpp v0, v0, v0 row_bcast:31 row_mask:0xc bank_mask:0xf
	s_nop 0
	v_readlane_b32 s100, v0, 63
	s_nop 1
	v_mov_b32_e32 v0, s100
	v_fmamk_f32 v0, v0, 0x3a800000, v201
	v_cmp_gt_f32_e32 vcc, s81, v0
	v_mul_f32_e32 v140, 0x4f800000, v0
	s_nop 0
	v_cndmask_b32_e32 v0, v0, v140, vcc
	v_sqrt_f32_e32 v140, v0
	s_nop 0
	v_add_u32_e32 v141, -1, v140
	v_fma_f32 v142, -v141, v140, v0
	v_cmp_ge_f32_e64 s[4:5], 0, v142
	v_add_u32_e32 v142, 1, v140
	s_nop 0
	v_cndmask_b32_e64 v141, v140, v141, s[4:5]
	v_fma_f32 v140, -v142, v140, v0
	v_cmp_lt_f32_e64 s[4:5], 0, v140
	s_nop 1
	v_cndmask_b32_e64 v140, v141, v142, s[4:5]
	v_mul_f32_e32 v141, 0x37800000, v140
	v_cndmask_b32_e32 v140, v140, v141, vcc
	v_cmp_class_f32_e32 vcc, v0, v202
	s_nop 1
	v_cndmask_b32_e32 v0, v140, v0, vcc
	v_div_scale_f32 v140, s[4:5], v0, v0, 1.0
	v_rcp_f32_e32 v141, v140
	s_nop 0
	v_fma_f32 v142, -v140, v141, 1.0
	v_fmac_f32_e32 v141, v142, v141
	v_div_scale_f32 v142, vcc, 1.0, v0, 1.0
	v_mul_f32_e32 v143, v142, v141
	v_fma_f32 v150, -v140, v143, v142
	v_fmac_f32_e32 v143, v150, v141
	v_fma_f32 v140, -v140, v143, v142
	v_div_fmas_f32 v140, v140, v141, v143
	v_div_fixup_f32 v0, v140, v0, 1.0
	v_pk_mul_f32 v[140:141], v[156:157], v[0:1] op_sel_hi:[1,0]
	v_pk_mul_f32 v[142:143], v[154:155], v[0:1] op_sel_hi:[1,0]
	v_pk_mul_f32 v[140:141], v[4:5], v[140:141]
	v_pk_mul_f32 v[142:143], v[2:3], v[142:143]
	v_pk_fma_f32 v[150:151], v[12:13], v[140:141], v[68:69]
	v_pk_fma_f32 v[152:153], v[10:11], v[142:143], v[66:67]
	v_pk_mul_f32 v[66:67], v[160:161], v[0:1] op_sel_hi:[1,0]
	v_pk_mul_f32 v[68:69], v[158:159], v[0:1] op_sel_hi:[1,0]
	v_pk_mul_f32 v[66:67], v[8:9], v[66:67]
	v_pk_mul_f32 v[68:69], v[6:7], v[68:69]
	v_pk_fma_f32 v[140:141], v[16:17], v[66:67], v[72:73]
	v_pk_fma_f32 v[142:143], v[14:15], v[68:69], v[70:71]
	v_pk_mul_f32 v[66:67], v[164:165], v[0:1] op_sel_hi:[1,0]
	v_pk_mul_f32 v[68:69], v[162:163], v[0:1] op_sel_hi:[1,0]
	v_pk_mul_f32 v[66:67], v[36:37], v[66:67]
	v_pk_mul_f32 v[68:69], v[34:35], v[68:69]
	v_pk_fma_f32 v[70:71], v[44:45], v[66:67], v[76:77]
	v_pk_fma_f32 v[72:73], v[42:43], v[68:69], v[74:75]
	v_pk_mul_f32 v[66:67], v[180:181], v[0:1] op_sel_hi:[1,0]
	v_pk_mul_f32 v[68:69], v[168:169], v[0:1] op_sel_hi:[1,0]
; __device__ __forceinline__ float wave_sum(float v) {
; #pragma unroll
;     for (int o = 1; o < 64; o <<= 1) v += __shfl_xor(v, o);
;     return v;
; }
; template <bool HAS_H, bool HAS_XN, int XL, int XS>
; __device__ __forceinline__ void rowwise_phase(const float* xf, half_t* x16, float* xo, const half_t* hs, const float* nwA, const float* gvec, const float* nwB, const float* scv, const float* shv, half_t* xn, int gw, int NW, int lane) {
;     ...
;             if (XS == 1) {
;                 u32x2* xs = (u32x2*)(x16 + (size_t)m * D) + lane;
; #pragma unroll
;                 for (int j = 0; j < 4; ++j) { u32x2 pk; pk.x = pg8::pkh(xv[j][0], xv[j][1]); pk.y = pg8::pkh(xv[j][2], xv[j][3]); xs[64 * j] = pk; }
;             } else if (XS == 2) {
;                 f32x4* xs = (f32x4*)(xo + (size_t)m * D) + lane;
; #pragma unroll
;                 for (int j = 0; j < 4; ++j) xs[64 * j] = xv[j];
;             }
;             if (HAS_XN) {
;                 float ss = 0.f;
; #pragma unroll
;                 for (int j = 0; j < 4; ++j) ss += (xv[j][0] * xv[j][0] + xv[j][1] * xv[j][1]) + (xv[j][2] * xv[j][2] + xv[j][3] * xv[j][3]);
;                 const float r = 1.0f / sqrtf(wave_sum(ss) * (1.f / D) + RMS_EPS);
;                 u32x2* xo2 = (u32x2*)(xn + (size_t)m * D) + lane;
; #pragma unroll
;                 for (int j = 0; j < 4; ++j) { const f32x4 o = (xv[j] * r * wB[j]) * sc1[j] + sh[j]; u32x2 pk; pk.x = pg8::pkh(o[0], o[1]); pk.y = pg8::pkh(o[2], o[3]); xo2[64 * j] = pk; }
	v_cvt_pk_f16_f32 v74, v152, v153
	v_cvt_pk_f16_f32 v75, v150, v151
	v_pk_mul_f32 v[68:69], v[38:39], v[68:69]
	v_pk_mul_f32 v[66:67], v[40:41], v[66:67]
	global_store_dwordx2 v[138:139], v[74:75], off
	v_cvt_pk_f16_f32 v74, v142, v143
	v_cvt_pk_f16_f32 v75, v140, v141
	v_pk_fma_f32 v[66:67], v[48:49], v[66:67], v[80:81]
	v_pk_fma_f32 v[68:69], v[46:47], v[68:69], v[78:79]
	global_store_dwordx2 v[138:139], v[74:75], off offset:512
	v_cvt_pk_f16_f32 v74, v72, v73
	v_cvt_pk_f16_f32 v75, v70, v71
	global_store_dwordx2 v[138:139], v[74:75], off offset:1024
	v_cvt_pk_f16_f32 v74, v68, v69
	v_cvt_pk_f16_f32 v75, v66, v67
	global_store_dwordx2 v[138:139], v[74:75], off offset:1536
	v_pk_mul_f32 v[74:75], v[150:151], v[150:151]
	v_pk_mul_f32 v[76:77], v[152:153], v[152:153]
	v_mul_f32_e32 v0, v72, v72
	v_pk_mov_b32 v[78:79], v[76:77], v[74:75] op_sel:[1,0]
	v_mov_b32_e32 v77, v75
	v_pk_add_f32 v[74:75], v[78:79], v[76:77]
	v_pk_mul_f32 v[76:77], v[140:141], v[140:141]
	v_pk_mul_f32 v[78:79], v[142:143], v[142:143]
	v_pk_add_f32 v[74:75], v[74:75], v[74:75] op_sel_hi:[0,1]
	v_pk_mov_b32 v[80:81], v[78:79], v[76:77] op_sel:[1,0]
	v_mov_b32_e32 v79, v77
	v_pk_add_f32 v[76:77], v[80:81], v[78:79]
	v_pk_fma_f32 v[78:79], v[72:73], v[72:73], v[0:1] op_sel_hi:[1,1,0]
	v_mul_f32_e32 v0, v70, v70
	v_pk_add_f32 v[76:77], v[76:77], v[76:77] op_sel_hi:[0,1]
	v_pk_fma_f32 v[80:81], v[70:71], v[70:71], v[0:1] op_sel_hi:[1,1,0]
	v_mul_f32_e32 v78, v68, v68
	v_mul_f32_e32 v80, v69, v69
	v_mul_f32_e32 v74, v66, v66
	v_mul_f32_e32 v76, v67, v67
	v_pk_add_f32 v[78:79], v[78:79], v[80:81]
	v_pk_add_f32 v[74:75], v[74:75], v[76:77]
	s_waitcnt vmcnt(0)
	v_mov_b32_e32 v80, v84
	v_pk_add_f32 v[74:75], v[78:79], v[74:75]
	v_mov_b32_e32 v81, v85
	v_add_f32_e32 v0, v74, v75
	s_nop 1
	v_add_f32_dpp v0, v0, v0 quad_perm:[1,0,3,2] row_mask:0xf bank_mask:0xf
	s_nop 1
	v_add_f32_dpp v0, v0, v0 quad_perm:[2,3,0,1] row_mask:0xf bank_mask:0xf
	s_nop 1
	v_add_f32_dpp v0, v0, v0 row_half_mirror row_mask:0xf bank_mask:0xf
	s_nop 1
	v_add_f32_dpp v0, v0, v0 row_mirror row_mask:0xf bank_mask:0xf
	s_nop 1
	v_add_f32_dpp v0, v0, v0 row_bcast:15 row_mask:0xa bank_mask:0xf
	s_nop 1
	v_add_f32_dpp v0, v0, v0 row_bcast:31 row_mask:0xc bank_mask:0xf
	s_nop 0
	v_readlane_b32 s100, v0, 63
	s_nop 1
	v_mov_b32_e32 v0, s100
	v_fmamk_f32 v0, v0, 0x3a800000, v201
	v_cmp_gt_f32_e32 vcc, s81, v0
	v_mul_f32_e32 v74, 0x4f800000, v0
	s_nop 0
	v_cndmask_b32_e32 v0, v0, v74, vcc
	v_sqrt_f32_e32 v74, v0
	s_nop 0
	v_add_u32_e32 v75, -1, v74
	v_fma_f32 v76, -v75, v74, v0
	v_cmp_ge_f32_e64 s[4:5], 0, v76
	v_add_u32_e32 v76, 1, v74
	s_nop 0
	v_cndmask_b32_e64 v75, v74, v75, s[4:5]
	v_fma_f32 v74, -v76, v74, v0
	v_cmp_lt_f32_e64 s[4:5], 0, v74
	s_nop 1
	v_cndmask_b32_e64 v74, v75, v76, s[4:5]
	v_mul_f32_e32 v75, 0x37800000, v74
	v_cndmask_b32_e32 v74, v74, v75, vcc
	v_cmp_class_f32_e32 vcc, v0, v202
	s_nop 1
	v_cndmask_b32_e32 v0, v74, v0, vcc
	v_div_scale_f32 v74, s[4:5], v0, v0, 1.0
	v_rcp_f32_e32 v75, v74
	s_nop 0
	v_fma_f32 v76, -v74, v75, 1.0
	v_fmac_f32_e32 v75, v76, v75
	v_div_scale_f32 v76, vcc, 1.0, v0, 1.0
	v_mul_f32_e32 v77, v76, v75
	v_fma_f32 v78, -v74, v77, v76
	v_fmac_f32_e32 v77, v78, v75
	v_fma_f32 v74, -v74, v77, v76
	v_div_fmas_f32 v74, v74, v75, v77
	v_div_fixup_f32 v0, v74, v0, 1.0
	v_pk_mul_f32 v[74:75], v[150:151], v[0:1] op_sel_hi:[1,0]
	v_pk_mul_f32 v[76:77], v[152:153], v[0:1] op_sel_hi:[1,0]
	v_pk_mul_f32 v[74:75], v[20:21], v[74:75]
	v_pk_mul_f32 v[76:77], v[18:19], v[76:77]
	v_pk_fma_f32 v[78:79], v[122:123], v[74:75], v[28:29]
	v_pk_fma_f32 v[74:75], v[124:125], v[76:77], v[26:27]
	v_add_co_u32_e32 v76, vcc, s57, v138
	v_cvt_pk_f16_f32 v74, v74, v75
	v_cvt_pk_f16_f32 v75, v78, v79
	v_addc_co_u32_e32 v77, vcc, -1, v139, vcc
	global_store_dwordx2 v[76:77], v[74:75], off
	v_pk_mul_f32 v[74:75], v[140:141], v[0:1] op_sel_hi:[1,0]
	v_pk_mul_f32 v[76:77], v[142:143], v[0:1] op_sel_hi:[1,0]
	v_pk_mul_f32 v[74:75], v[24:25], v[74:75]
	v_pk_mul_f32 v[76:77], v[22:23], v[76:77]
	v_pk_fma_f32 v[74:75], v[126:127], v[74:75], v[32:33]
	v_pk_fma_f32 v[76:77], v[128:129], v[76:77], v[30:31]
	v_pk_mul_f32 v[70:71], v[70:71], v[0:1] op_sel_hi:[1,0]
	v_pk_mul_f32 v[72:73], v[72:73], v[0:1] op_sel_hi:[1,0]
	v_cvt_pk_f16_f32 v76, v76, v77
	v_cvt_pk_f16_f32 v77, v74, v75
	v_add_co_u32_e32 v74, vcc, s67, v138
	v_pk_mul_f32 v[72:73], v[50:51], v[72:73]
	v_pk_mul_f32 v[70:71], v[52:53], v[70:71]
	v_addc_co_u32_e32 v75, vcc, -1, v139, vcc
	v_pk_fma_f32 v[70:71], v[130:131], v[70:71], v[60:61]
	v_pk_fma_f32 v[72:73], v[132:133], v[72:73], v[58:59]
	v_pk_mul_f32 v[66:67], v[66:67], v[0:1] op_sel_hi:[1,0]
	v_pk_mul_f32 v[68:69], v[68:69], v[0:1] op_sel_hi:[1,0]
	v_cvt_pk_f16_f32 v72, v72, v73
	v_cvt_pk_f16_f32 v73, v70, v71
	v_add_co_u32_e32 v70, vcc, s95, v138
	v_pk_mul_f32 v[68:69], v[54:55], v[68:69]
	v_pk_mul_f32 v[66:67], v[56:57], v[66:67]
	v_addc_co_u32_e32 v71, vcc, -1, v139, vcc
	v_pk_fma_f32 v[66:67], v[134:135], v[66:67], v[64:65]
	v_pk_fma_f32 v[68:69], v[136:137], v[68:69], v[62:63]
	global_store_dwordx2 v[74:75], v[76:77], off
	v_cvt_pk_f16_f32 v68, v68, v69
	v_cvt_pk_f16_f32 v69, v66, v67
	v_add_co_u32_e32 v66, vcc, s76, v138
	global_store_dwordx2 v[70:71], v[72:73], off
	s_nop 0
	v_addc_co_u32_e32 v67, vcc, -1, v139, vcc
	global_store_dwordx2 v[66:67], v[68:69], off
	v_mov_b32_e32 v66, v94
	v_mov_b32_e32 v67, v95
	v_mov_b32_e32 v68, v96
	v_mov_b32_e32 v69, v97
	v_mov_b32_e32 v70, v90
	v_mov_b32_e32 v71, v91
	v_mov_b32_e32 v72, v92
	v_mov_b32_e32 v73, v93
	v_mov_b32_e32 v74, v86
	v_mov_b32_e32 v75, v87
	v_mov_b32_e32 v76, v88
	v_mov_b32_e32 v77, v89
	v_mov_b32_e32 v78, v82
	v_mov_b32_e32 v79, v83
	v_lshl_add_u64 v[138:139], v[138:139], 0, s[90:91]
	s_cbranch_scc0 .LBB0_1243
	s_branch .LBB0_1238

; __device__ __forceinline__ float wave_sum(float v) {
; #pragma unroll
;     for (int o = 1; o < 64; o <<= 1) v += __shfl_xor(v, o);
;     return v;
; }
; template <bool HAS_H, bool HAS_XN, int XL, int XS>
; __device__ __forceinline__ void rowwise_phase(const float* xf, half_t* x16, float* xo, const half_t* hs, const float* nwA, const float* gvec, const float* nwB, const float* scv, const float* shv, half_t* xn, int gw, int NW, int lane) {
;     ...
;         for (int m = b * S + gw; m < mend; m += NW) {
;             f32x4 xv[4]; half4 hcur[4];
; #pragma unroll
;             for (int j = 0; j < 4; ++j) { if (XL == 0) xv[j] = xq[j]; else xv[j] = (f32x4){(float)xh[j][0], (float)xh[j][1], (float)xh[j][2], (float)xh[j][3]}; if (HAS_H) hcur[j] = hq[j]; }
;             const int mn = (m + NW < mend) ? m + NW : m;
;             {
;                 if (XL == 0) { const f32x4* xr = (const f32x4*)(xf + (size_t)mn * D) + lane;
; #pragma unroll
;                     for (int j = 0; j < 4; ++j) xq[j] = xr[64 * j]; }
;                 else { const half4* xr = (const half4*)(x16 + (size_t)mn * D) + lane;
; #pragma unroll
;                     for (int j = 0; j < 4; ++j) xh[j] = xr[64 * j]; }
;                 if (HAS_H) { const half4* hr = (const half4*)(hs + (size_t)mn * D) + lane;
; #pragma unroll
;                     for (int j = 0; j < 4; ++j) hq[j] = hr[64 * j]; }
;             }
;             if (HAS_H) {
;                 f32x4 hv[4]; float ss = 0.f;
; #pragma unroll
;                 for (int j = 0; j < 4; ++j) { const half4 h4 = hcur[j]; hv[j] = (f32x4){(float)h4[0], (float)h4[1], (float)h4[2], (float)h4[3]}; ss += (hv[j][0] * hv[j][0] + hv[j][1] * hv[j][1]) + (hv[j][2] * hv[j][2] + hv[j][3] * hv[j][3]); }
;                 const float r = 1.0f / sqrtf(wave_sum(ss) * (1.f / D) + RMS_EPS);
; #pragma unroll
;                 for (int j = 0; j < 4; ++j) xv[j] = xv[j] + gg[j] * (hv[j] * r * wA[j]);
;             }
;             if (XS == 1) {
;                 u32x2* xs = (u32x2*)(x16 + (size_t)m * D) + lane;
; #pragma unroll
;                 for (int j = 0; j < 4; ++j) { u32x2 pk; pk.x = pg8::pkh(xv[j][0], xv[j][1]); pk.y = pg8::pkh(xv[j][2], xv[j][3]); xs[64 * j] = pk; }
;             } else if (XS == 2) {
;                 f32x4* xs = (f32x4*)(xo + (size_t)m * D) + lane;
; #pragma unroll
;                 for (int j = 0; j < 4; ++j) xs[64 * j] = xv[j];
.LBB0_1549:
	v_cvt_f32_f16_sdwa v93, v58 dst_sel:DWORD dst_unused:UNUSED_PAD src0_sel:WORD_1
	v_cvt_f32_f16_sdwa v95, v59 dst_sel:DWORD dst_unused:UNUSED_PAD src0_sel:WORD_1
	v_cvt_f32_f16_e32 v92, v58
	v_cvt_f32_f16_e32 v94, v59
	v_mov_b32_e32 v96, v93
	v_mov_b32_e32 v97, v95
	v_mov_b32_e32 v58, v92
	v_mov_b32_e32 v59, v94
	v_pk_mul_f32 v[96:97], v[96:97], v[96:97]
	v_cvt_f32_f16_sdwa v99, v57 dst_sel:DWORD dst_unused:UNUSED_PAD src0_sel:WORD_1
	v_pk_fma_f32 v[58:59], v[58:59], v[58:59], v[96:97]
	v_cvt_f32_f16_sdwa v97, v56 dst_sel:DWORD dst_unused:UNUSED_PAD src0_sel:WORD_1
	v_cvt_f32_f16_e32 v96, v56
	v_cvt_f32_f16_e32 v98, v57
	v_mov_b32_e32 v101, v99
	v_mov_b32_e32 v100, v97
	s_add_i32 s3, s2, s80
	v_mov_b32_e32 v56, v96
	v_mov_b32_e32 v57, v98
	v_pk_mul_f32 v[100:101], v[100:101], v[100:101]
	s_cmp_lt_i32 s3, s10
	v_pk_fma_f32 v[56:57], v[56:57], v[56:57], v[100:101]
	v_cvt_f32_f16_e32 v100, v54
	s_cselect_b32 s4, s3, s2
	v_cvt_f32_f16_sdwa v101, v54 dst_sel:DWORD dst_unused:UNUSED_PAD src0_sel:WORD_1
	s_ashr_i32 s5, s4, 31
	v_cvt_f32_f16_e32 v102, v55
	s_lshl_b64 s[4:5], s[4:5], 11
	v_cvt_f32_f16_sdwa v103, v55 dst_sel:DWORD dst_unused:UNUSED_PAD src0_sel:WORD_1
	v_cvt_f32_f16_sdwa v107, v52 dst_sel:DWORD dst_unused:UNUSED_PAD src0_sel:WORD_1
	v_cvt_f32_f16_e32 v106, v52
	v_cvt_f32_f16_sdwa v109, v53 dst_sel:DWORD dst_unused:UNUSED_PAD src0_sel:WORD_1
	v_cvt_f32_f16_e32 v108, v53
	v_cvt_f32_f16_sdwa v71, v46 dst_sel:DWORD dst_unused:UNUSED_PAD src0_sel:WORD_1
	v_cvt_f32_f16_e32 v70, v46
	v_lshl_add_u64 v[46:47], v[38:39], 0, s[4:5]
	v_lshl_add_u64 v[84:85], v[40:41], 0, s[4:5]
	v_mul_f32_e32 v54, v100, v100
	v_cvt_f32_f16_sdwa v63, v48 dst_sel:DWORD dst_unused:UNUSED_PAD src0_sel:WORD_1
	v_cvt_f32_f16_e32 v62, v48
	v_cvt_f32_f16_sdwa v69, v49 dst_sel:DWORD dst_unused:UNUSED_PAD src0_sel:WORD_1
	v_cvt_f32_f16_e32 v68, v49
	v_cvt_f32_f16_sdwa v65, v50 dst_sel:DWORD dst_unused:UNUSED_PAD src0_sel:WORD_1
	v_cvt_f32_f16_e32 v64, v50
	v_cvt_f32_f16_sdwa v73, v51 dst_sel:DWORD dst_unused:UNUSED_PAD src0_sel:WORD_1
	v_cvt_f32_f16_e32 v72, v51
	v_cvt_f32_f16_sdwa v67, v44 dst_sel:DWORD dst_unused:UNUSED_PAD src0_sel:WORD_1
	v_cvt_f32_f16_e32 v66, v44
	v_cvt_f32_f16_sdwa v75, v45 dst_sel:DWORD dst_unused:UNUSED_PAD src0_sel:WORD_1
	v_cvt_f32_f16_e32 v74, v45
	global_load_dwordx2 v[48:49], v[46:47], off
	global_load_dwordx2 v[50:51], v[46:47], off offset:512
	global_load_dwordx2 v[44:45], v[46:47], off offset:1024
	s_nop 0
	global_load_dwordx2 v[46:47], v[46:47], off offset:1536
	s_nop 0
	global_load_dwordx2 v[86:87], v[84:85], off
	global_load_dwordx2 v[88:89], v[84:85], off offset:512
	global_load_dwordx2 v[90:91], v[84:85], off offset:1024
	s_nop 0
	global_load_dwordx2 v[84:85], v[84:85], off offset:1536
	v_pk_fma_f32 v[54:55], v[100:101], v[100:101], v[54:55] op_sel_hi:[1,1,0]
	v_pk_add_f32 v[58:59], v[58:59], v[58:59] op_sel_hi:[0,1]
	v_mul_f32_e32 v54, v102, v102
	v_pk_add_f32 v[56:57], v[56:57], v[56:57] op_sel_hi:[0,1]
	v_pk_fma_f32 v[104:105], v[102:103], v[102:103], v[54:55] op_sel_hi:[1,1,0]
	v_pk_mul_f32 v[52:53], v[106:107], v[106:107]
	v_pk_mul_f32 v[110:111], v[108:109], v[108:109]
	v_mov_b32_e32 v54, v52
	v_mov_b32_e32 v104, v53
	v_mov_b32_e32 v58, v110
	v_mov_b32_e32 v56, v111
	v_pk_add_f32 v[52:53], v[54:55], v[104:105]
	v_pk_add_f32 v[54:55], v[58:59], v[56:57]
	v_cvt_f32_f16_sdwa v83, v81 dst_sel:DWORD dst_unused:UNUSED_PAD src0_sel:WORD_1
	v_pk_add_f32 v[52:53], v[52:53], v[54:55]
	v_cvt_f32_f16_e32 v82, v81
	v_add_f32_e32 v52, v52, v53
	s_cmp_ge_i32 s3, s10
	s_mov_b32 s2, s3
	s_nop 1
	v_add_f32_dpp v52, v52, v52 quad_perm:[1,0,3,2] row_mask:0xf bank_mask:0xf
	s_nop 1
	v_add_f32_dpp v52, v52, v52 quad_perm:[2,3,0,1] row_mask:0xf bank_mask:0xf
	s_nop 1
	v_add_f32_dpp v52, v52, v52 row_half_mirror row_mask:0xf bank_mask:0xf
	s_nop 1
	v_add_f32_dpp v52, v52, v52 row_mirror row_mask:0xf bank_mask:0xf
	s_nop 1
	v_add_f32_dpp v52, v52, v52 row_bcast:15 row_mask:0xa bank_mask:0xf
	s_nop 1
	v_add_f32_dpp v52, v52, v52 row_bcast:31 row_mask:0xc bank_mask:0xf
	s_nop 0
	v_readlane_b32 s100, v52, 63
	s_nop 1
	v_mov_b32_e32 v52, s100
	v_fmamk_f32 v52, v52, 0x3a800000, v201
	v_cmp_gt_f32_e32 vcc, s81, v52
	v_mul_f32_e32 v53, 0x4f800000, v52
	s_waitcnt vmcnt(0)
	v_mov_b32_e32 v81, v47
	v_cndmask_b32_e32 v52, v52, v53, vcc
	v_sqrt_f32_e32 v53, v52
	s_nop 0
	v_add_u32_e32 v54, -1, v53
	v_fma_f32 v55, -v54, v53, v52
	v_cmp_ge_f32_e64 s[4:5], 0, v55
	v_add_u32_e32 v55, 1, v53
	s_nop 0
	v_cndmask_b32_e64 v54, v53, v54, s[4:5]
	v_fma_f32 v53, -v55, v53, v52
	v_cmp_lt_f32_e64 s[4:5], 0, v53
	s_nop 1
	v_cndmask_b32_e64 v53, v54, v55, s[4:5]
	v_mul_f32_e32 v54, 0x37800000, v53
	v_cndmask_b32_e32 v53, v53, v54, vcc
	v_cmp_class_f32_e32 vcc, v52, v202
	s_nop 1
	v_cndmask_b32_e32 v52, v53, v52, vcc
	v_div_scale_f32 v53, s[4:5], v52, v52, 1.0
	v_rcp_f32_e32 v54, v53
	s_nop 0
	v_fma_f32 v55, -v53, v54, 1.0
	v_fmac_f32_e32 v54, v55, v54
	v_div_scale_f32 v55, vcc, 1.0, v52, 1.0
	v_mul_f32_e32 v56, v55, v54
	v_fma_f32 v57, -v53, v56, v55
	v_fmac_f32_e32 v56, v57, v54
	v_fma_f32 v53, -v53, v56, v55
	v_div_fmas_f32 v53, v53, v54, v56
	v_div_fixup_f32 v104, v53, v52, 1.0
	v_pk_mul_f32 v[52:53], v[94:95], v[104:105] op_sel_hi:[1,0]
	v_pk_mul_f32 v[54:55], v[92:93], v[104:105] op_sel_hi:[1,0]
	v_pk_mul_f32 v[52:53], v[4:5], v[52:53]
	v_pk_mul_f32 v[56:57], v[2:3], v[54:55]
	v_pk_fma_f32 v[54:55], v[12:13], v[52:53], v[68:69]
	v_pk_fma_f32 v[52:53], v[10:11], v[56:57], v[62:63]
	v_pk_mul_f32 v[56:57], v[98:99], v[104:105] op_sel_hi:[1,0]
	v_pk_mul_f32 v[58:59], v[96:97], v[104:105] op_sel_hi:[1,0]
	v_pk_mul_f32 v[56:57], v[8:9], v[56:57]
	v_pk_mul_f32 v[62:63], v[6:7], v[58:59]
	v_pk_fma_f32 v[58:59], v[16:17], v[56:57], v[72:73]
	v_pk_fma_f32 v[56:57], v[14:15], v[62:63], v[64:65]
	v_pk_mul_f32 v[62:63], v[102:103], v[104:105] op_sel_hi:[1,0]
	v_pk_mul_f32 v[64:65], v[100:101], v[104:105] op_sel_hi:[1,0]
	v_pk_mul_f32 v[62:63], v[20:21], v[62:63]
	v_pk_mul_f32 v[68:69], v[18:19], v[64:65]
	v_pk_fma_f32 v[64:65], v[28:29], v[62:63], v[74:75]
	v_pk_fma_f32 v[62:63], v[26:27], v[68:69], v[66:67]
	v_pk_mul_f32 v[66:67], v[108:109], v[104:105] op_sel_hi:[1,0]
	v_pk_mul_f32 v[68:69], v[106:107], v[104:105] op_sel_hi:[1,0]
	v_pk_mul_f32 v[66:67], v[24:25], v[66:67]
	v_pk_mul_f32 v[72:73], v[22:23], v[68:69]
	v_pk_fma_f32 v[68:69], v[32:33], v[66:67], v[82:83]
	v_pk_fma_f32 v[66:67], v[30:31], v[72:73], v[70:71]
	global_store_dwordx4 v[60:61], v[52:55], off offset:-2048
	global_store_dwordx4 v[60:61], v[56:59], off offset:-1024
	global_store_dwordx4 v[60:61], v[62:65], off
	global_store_dwordx4 v[60:61], v[66:69], off offset:1024
	v_mov_b32_e32 v58, v86
	v_mov_b32_e32 v59, v87
	v_mov_b32_e32 v56, v88
	v_mov_b32_e32 v57, v89
	v_mov_b32_e32 v54, v90
	v_mov_b32_e32 v55, v91
	v_mov_b32_e32 v52, v84
	v_mov_b32_e32 v53, v85
	v_lshl_add_u64 v[60:61], v[60:61], 0, s[58:59]
	s_cbranch_scc0 .LBB0_1549
	s_branch .LBB0_1544
